# prompt-attention output: 64 two-byte stores per wave replaced by an LDS transpose tile + 8 global_store_dwordx4 per wave (store-issue-bound tail, asm guide 7.3)
# speedup vs baseline: 1.0278x; 1.0069x over previous
.LBB0_496:
	s_or_b64 exec, exec, s[4:5]
	s_movk_i32 s4, 0x100
	v_cmp_gt_u32_e32 vcc, s4, v148
	s_waitcnt lgkmcnt(0)
	s_barrier
	s_and_saveexec_b64 s[64:65], vcc
	s_cbranch_execz .LBB0_459
	ds_read2st64_b32 v[8:9], v57 offset1:1
	ds_read2st64_b32 v[10:11], v57 offset0:2 offset1:3
	ds_read2st64_b32 v[12:13], v57 offset0:4 offset1:5
	ds_read2st64_b32 v[26:27], v57 offset0:6 offset1:7
	s_lshl_b32 s4, s91, 11
	s_add_u32 s4, s84, s4
	s_waitcnt lgkmcnt(2)
	v_fma_f32 v15, -v140, v10, v33
	v_fma_f32 v16, -v140, v9, v16
	s_waitcnt lgkmcnt(0)
	v_fma_f32 v9, -v140, v26, v5
	v_fma_f32 v7, -v140, v27, v6
	ds_read2st64_b32 v[26:27], v57 offset0:8 offset1:9
	ds_read2st64_b32 v[28:29], v57 offset0:10 offset1:11
	ds_read2st64_b32 v[30:31], v57 offset0:12 offset1:13
	ds_read2st64_b32 v[44:45], v57 offset0:14 offset1:15
	v_fma_f32 v17, -v140, v8, v68
	v_fma_f32 v14, -v140, v11, v69
	v_fma_f32 v10, -v140, v13, v71
	s_waitcnt lgkmcnt(3)
	v_fma_f32 v13, -v140, v26, v0
	v_fma_f32 v11, -v140, v27, v1
	s_waitcnt lgkmcnt(2)
	v_fma_f32 v8, -v140, v28, v2
	v_fma_f32 v6, -v140, v29, v3
	s_waitcnt lgkmcnt(1)
	v_fma_f32 v5, -v140, v30, v4
	v_fma_f32 v4, -v140, v31, v24
	s_waitcnt lgkmcnt(0)
	v_fma_f32 v3, -v140, v44, v23
	v_fma_f32 v2, -v140, v45, v25
	ds_read2st64_b32 v[24:25], v57 offset0:16 offset1:17
	ds_read2st64_b32 v[26:27], v57 offset0:18 offset1:19
	ds_read2st64_b32 v[28:29], v57 offset0:20 offset1:21
	ds_read2st64_b32 v[44:45], v57 offset0:22 offset1:23
	v_fma_f32 v90, v17, v17, 0
	s_addc_u32 s5, s85, 0
	s_waitcnt lgkmcnt(2)
	v_fma_f32 v30, -v140, v27, v96
	v_fma_f32 v33, -v140, v24, v32
	s_waitcnt lgkmcnt(0)
	v_fma_f32 v24, -v140, v44, v97
	v_fma_f32 v22, -v140, v45, v22
	ds_read2st64_b32 v[44:45], v57 offset0:24 offset1:25
	ds_read2st64_b32 v[46:47], v57 offset0:26 offset1:27
	ds_read2st64_b32 v[62:63], v57 offset0:28 offset1:29
	ds_read2st64_b32 v[96:97], v57 offset0:30 offset1:31
	v_fma_f32 v32, -v140, v25, v49
	v_fma_f32 v31, -v140, v26, v95
	v_fma_f32 v26, -v140, v29, v99
	s_waitcnt lgkmcnt(3)
	v_fma_f32 v29, -v140, v44, v18
	v_fma_f32 v27, -v140, v45, v19
	s_waitcnt lgkmcnt(2)
	v_fma_f32 v25, -v140, v46, v20
	v_fma_f32 v23, -v140, v47, v21
	s_waitcnt lgkmcnt(1)
	v_fma_f32 v21, -v140, v62, v40
	v_fma_f32 v20, -v140, v63, v43
	s_waitcnt lgkmcnt(0)
	v_fma_f32 v19, -v140, v96, v41
	v_fma_f32 v18, -v140, v97, v42
	ds_read2st64_b32 v[40:41], v57 offset0:32 offset1:33
	ds_read2st64_b32 v[42:43], v57 offset0:34 offset1:35
	ds_read2st64_b32 v[44:45], v57 offset0:36 offset1:37
	ds_read2st64_b32 v[62:63], v57 offset0:38 offset1:39
	v_fmac_f32_e32 v90, v33, v33
	s_lshl_b32 s6, s15, 1
	s_waitcnt lgkmcnt(2)
	v_fma_f32 v47, -v140, v42, v91
	v_fma_f32 v49, -v140, v40, v48
	v_fma_f32 v46, -v140, v43, v92
	s_waitcnt lgkmcnt(1)
	v_fma_f32 v44, -v140, v44, v93
	v_fma_f32 v42, -v140, v45, v94
	s_waitcnt lgkmcnt(0)
	v_fma_f32 v40, -v140, v62, v38
	v_fma_f32 v38, -v140, v63, v39
	ds_read2st64_b32 v[62:63], v57 offset0:40 offset1:41
	ds_read2st64_b32 v[92:93], v57 offset0:42 offset1:43
	ds_read2st64_b32 v[94:95], v57 offset0:44 offset1:45
	ds_read2st64_b32 v[96:97], v57 offset0:46 offset1:47
	v_fma_f32 v48, -v140, v41, v67
	v_fmac_f32_e32 v90, v49, v49
	s_waitcnt lgkmcnt(2)
	v_fma_f32 v41, -v140, v92, v36
	v_fma_f32 v45, -v140, v62, v34
	v_fma_f32 v43, -v140, v63, v35
	v_fma_f32 v39, -v140, v93, v37
	s_waitcnt lgkmcnt(1)
	v_fma_f32 v37, -v140, v94, v56
	v_fma_f32 v36, -v140, v95, v60
	s_waitcnt lgkmcnt(0)
	v_fma_f32 v35, -v140, v96, v58
	v_fma_f32 v34, -v140, v97, v59
	ds_read2st64_b32 v[58:59], v57 offset0:48 offset1:49
	ds_read2st64_b32 v[60:61], v57 offset0:50 offset1:51
	ds_read2st64_b32 v[92:93], v57 offset0:52 offset1:53
	ds_read2st64_b32 v[94:95], v57 offset0:54 offset1:55
	s_add_u32 s66, s4, s6
	v_fma_f32 v85, v16, v16, 0
	s_waitcnt lgkmcnt(2)
	v_fma_f32 v63, -v140, v60, v84
	v_fma_f32 v67, -v140, v58, v66
	v_fma_f32 v62, -v140, v61, v86
	s_waitcnt lgkmcnt(1)
	v_fma_f32 v60, -v140, v92, v87
	v_fma_f32 v58, -v140, v93, v88
	s_waitcnt lgkmcnt(0)
	v_fma_f32 v56, -v140, v94, v53
	v_fma_f32 v53, -v140, v95, v89
	ds_read2st64_b32 v[86:87], v57 offset0:56 offset1:57
	ds_read2st64_b32 v[88:89], v57 offset0:58 offset1:59
	ds_read2st64_b32 v[92:93], v57 offset0:60 offset1:61
	ds_read2st64_b32 v[94:95], v57 offset0:62 offset1:63
	v_fmac_f32_e32 v90, v67, v67
	v_fma_f32 v66, -v140, v59, v83
	s_waitcnt lgkmcnt(2)
	v_fma_f32 v57, -v140, v88, v55
	v_add_f32_dpp v55, v90, v90 quad_perm:[1,0,3,2] row_mask:0xf bank_mask:0xf bound_ctrl:1
	v_fma_f32 v59, -v140, v87, v54
	v_fma_f32 v54, -v140, v89, v81
	v_add_f32_dpp v55, v55, v55 quad_perm:[2,3,0,1] row_mask:0xf bank_mask:0xf bound_ctrl:1
	v_fma_f32 v61, -v140, v86, v50
	s_waitcnt lgkmcnt(1)
	v_fma_f32 v50, -v140, v92, v82
	v_add_f32_dpp v55, v55, v55 row_half_mirror row_mask:0xf bank_mask:0xf bound_ctrl:1
	s_addc_u32 s67, s5, 0
	v_fmac_f32_e32 v85, v32, v32
	v_add_f32_dpp v55, v55, v55 row_ror:8 row_mask:0xf bank_mask:0xf bound_ctrl:1
	v_mov_b32_e32 v81, v55
	s_nop 1
	v_permlane16_swap_b32_e32 v55, v81
	v_add_f32_e32 v55, v55, v81
	v_fmamk_f32 v55, v55, 0x3c000000, v141
	v_mul_f32_e32 v81, 0x4f800000, v55
	v_cmp_gt_f32_e32 vcc, s86, v55
	v_fmac_f32_e32 v85, v48, v48
	v_fmac_f32_e32 v85, v66, v66
	v_cndmask_b32_e32 v81, v55, v81, vcc
	v_sqrt_f32_e32 v82, v81
	v_fma_f32 v55, -v140, v93, v51
	s_waitcnt lgkmcnt(0)
	v_fma_f32 v51, -v140, v94, v72
	v_add_f32_dpp v85, v85, v85 quad_perm:[1,0,3,2] row_mask:0xf bank_mask:0xf bound_ctrl:1
	v_add_u32_e32 v72, -1, v82
	v_fma_f32 v83, -v72, v82, v81
	v_cmp_ge_f32_e64 s[4:5], 0, v83
	v_add_u32_e32 v83, 1, v82
	v_add_f32_dpp v85, v85, v85 quad_perm:[2,3,0,1] row_mask:0xf bank_mask:0xf bound_ctrl:1
	v_cndmask_b32_e64 v72, v82, v72, s[4:5]
	v_fma_f32 v82, -v83, v82, v81
	v_cmp_lt_f32_e64 s[4:5], 0, v82
	v_add_f32_dpp v85, v85, v85 row_half_mirror row_mask:0xf bank_mask:0xf bound_ctrl:1
	v_fma_f32 v73, v15, v15, 0
	v_cndmask_b32_e64 v72, v72, v83, s[4:5]
	v_mul_f32_e32 v82, 0x37800000, v72
	v_cndmask_b32_e32 v72, v72, v82, vcc
	v_cmp_class_f32_e32 vcc, v81, v142
	v_add_f32_dpp v85, v85, v85 row_ror:8 row_mask:0xf bank_mask:0xf bound_ctrl:1
	v_mov_b32_e32 v86, v85
	v_cndmask_b32_e32 v72, v72, v81, vcc
	v_div_scale_f32 v81, s[4:5], v72, v72, s87
	v_rcp_f32_e32 v82, v81
	v_permlane16_swap_b32_e32 v85, v86
	v_add_f32_e32 v85, v85, v86
	v_fmamk_f32 v85, v85, 0x3c000000, v141
	v_mul_f32_e32 v86, 0x4f800000, v85
	v_cmp_gt_f32_e64 s[4:5], s86, v85
	v_fma_f32 v83, -v81, v82, 1.0
	v_fmac_f32_e32 v82, v83, v82
	v_cndmask_b32_e64 v85, v85, v86, s[4:5]
	v_div_scale_f32 v83, vcc, s87, v72, s87
	v_sqrt_f32_e32 v86, v85
	v_mul_f32_e32 v84, v83, v82
	v_fma_f32 v87, -v81, v84, v83
	v_fmac_f32_e32 v84, v87, v82
	v_fma_f32 v81, -v81, v84, v83
	v_add_u32_e32 v83, -1, v86
	v_fma_f32 v87, -v83, v86, v85
	v_fmac_f32_e32 v73, v31, v31
	v_cmp_ge_f32_e64 s[6:7], 0, v87
	v_add_u32_e32 v87, 1, v86
	v_fmac_f32_e32 v73, v47, v47
	v_cndmask_b32_e64 v83, v86, v83, s[6:7]
	v_fma_f32 v86, -v87, v86, v85
	v_fmac_f32_e32 v73, v63, v63
	v_cmp_lt_f32_e64 s[6:7], 0, v86
	v_div_fmas_f32 v81, v81, v82, v84
	v_add_f32_dpp v73, v73, v73 quad_perm:[1,0,3,2] row_mask:0xf bank_mask:0xf bound_ctrl:1
	v_cndmask_b32_e64 v83, v83, v87, s[6:7]
	v_mul_f32_e32 v86, 0x37800000, v83
	v_add_f32_dpp v73, v73, v73 quad_perm:[2,3,0,1] row_mask:0xf bank_mask:0xf bound_ctrl:1
	v_cndmask_b32_e64 v83, v83, v86, s[4:5]
	v_cmp_class_f32_e64 s[4:5], v85, v142
	v_add_f32_dpp v73, v73, v73 row_half_mirror row_mask:0xf bank_mask:0xf bound_ctrl:1
	v_div_fixup_f32 v72, v81, v72, s87
	v_cndmask_b32_e64 v83, v83, v85, s[4:5]
	v_add_f32_dpp v73, v73, v73 row_ror:8 row_mask:0xf bank_mask:0xf bound_ctrl:1
	v_div_scale_f32 v85, s[4:5], v83, v83, s87
	v_mov_b32_e32 v84, v73
	v_rcp_f32_e32 v86, v85
	s_nop 0
	v_permlane16_swap_b32_e32 v73, v84
	v_add_f32_e32 v73, v73, v84
	v_fmamk_f32 v73, v73, 0x3c000000, v141
	v_mul_f32_e32 v84, 0x4f800000, v73
	v_cmp_gt_f32_e64 s[4:5], s86, v73
	v_fma_f32 v81, -v85, v86, 1.0
	v_fmac_f32_e32 v86, v81, v86
	v_cndmask_b32_e64 v73, v73, v84, s[4:5]
	v_div_scale_f32 v81, vcc, s87, v83, s87
	v_sqrt_f32_e32 v84, v73
	v_mul_f32_e32 v82, v81, v86
	v_fma_f32 v87, -v85, v82, v81
	v_fmac_f32_e32 v82, v87, v86
	v_fma_f32 v81, -v85, v82, v81
	v_add_u32_e32 v85, -1, v84
	v_fma_f32 v75, v14, v14, 0
	v_fma_f32 v87, -v85, v84, v73
	v_fmac_f32_e32 v75, v30, v30
	v_cmp_ge_f32_e64 s[6:7], 0, v87
	v_add_u32_e32 v87, 1, v84
	v_fmac_f32_e32 v75, v46, v46
	v_cndmask_b32_e64 v85, v84, v85, s[6:7]
	v_fma_f32 v84, -v87, v84, v73
	v_fmac_f32_e32 v75, v62, v62
	v_cmp_lt_f32_e64 s[6:7], 0, v84
	v_fma_f32 v12, -v140, v12, v70
	v_add_f32_dpp v75, v75, v75 quad_perm:[1,0,3,2] row_mask:0xf bank_mask:0xf bound_ctrl:1
	v_cndmask_b32_e64 v84, v85, v87, s[6:7]
	v_mul_f32_e32 v85, 0x37800000, v84
	v_add_f32_dpp v75, v75, v75 quad_perm:[2,3,0,1] row_mask:0xf bank_mask:0xf bound_ctrl:1
	v_cndmask_b32_e64 v84, v84, v85, s[4:5]
	v_cmp_class_f32_e64 s[4:5], v73, v142
	v_add_f32_dpp v75, v75, v75 row_half_mirror row_mask:0xf bank_mask:0xf bound_ctrl:1
	v_fma_f32 v77, v12, v12, 0
	v_cndmask_b32_e64 v84, v84, v73, s[4:5]
	v_div_fmas_f32 v73, v81, v86, v82
	v_add_f32_dpp v75, v75, v75 row_ror:8 row_mask:0xf bank_mask:0xf bound_ctrl:1
	v_div_scale_f32 v85, s[4:5], v84, v84, s87
	v_div_fixup_f32 v73, v73, v83, s87
	v_mov_b32_e32 v83, v75
	v_rcp_f32_e32 v87, v85
	s_nop 0
	v_permlane16_swap_b32_e32 v75, v83
	v_add_f32_e32 v75, v75, v83
	v_fmamk_f32 v75, v75, 0x3c000000, v141
	v_mul_f32_e32 v83, 0x4f800000, v75
	v_cmp_gt_f32_e64 s[4:5], s86, v75
	v_fma_f32 v81, -v85, v87, 1.0
	v_fmac_f32_e32 v87, v81, v87
	v_cndmask_b32_e64 v75, v75, v83, s[4:5]
	v_div_scale_f32 v81, vcc, s87, v84, s87
	v_sqrt_f32_e32 v83, v75
	v_mul_f32_e32 v82, v81, v87
	v_fma_f32 v86, -v85, v82, v81
	v_fmac_f32_e32 v82, v86, v87
	v_fma_f32 v81, -v85, v82, v81
	v_add_u32_e32 v85, -1, v83
	v_fma_f32 v28, -v140, v28, v98
	v_fma_f32 v86, -v85, v83, v75
	v_fmac_f32_e32 v77, v28, v28
	v_cmp_ge_f32_e64 s[6:7], 0, v86
	v_add_u32_e32 v86, 1, v83
	v_fmac_f32_e32 v77, v44, v44
	v_cndmask_b32_e64 v85, v83, v85, s[6:7]
	v_fma_f32 v83, -v86, v83, v75
	v_fmac_f32_e32 v77, v60, v60
	v_cmp_lt_f32_e64 s[6:7], 0, v83
	v_fma_f32 v79, v10, v10, 0
	v_add_f32_dpp v77, v77, v77 quad_perm:[1,0,3,2] row_mask:0xf bank_mask:0xf bound_ctrl:1
	v_cndmask_b32_e64 v83, v85, v86, s[6:7]
	v_mul_f32_e32 v85, 0x37800000, v83
	v_add_f32_dpp v77, v77, v77 quad_perm:[2,3,0,1] row_mask:0xf bank_mask:0xf bound_ctrl:1
	v_cndmask_b32_e64 v83, v83, v85, s[4:5]
	v_cmp_class_f32_e64 s[4:5], v75, v142
	v_add_f32_dpp v77, v77, v77 row_half_mirror row_mask:0xf bank_mask:0xf bound_ctrl:1
	v_fmac_f32_e32 v79, v26, v26
	v_cndmask_b32_e64 v83, v83, v75, s[4:5]
	v_div_fmas_f32 v75, v81, v87, v82
	v_add_f32_dpp v77, v77, v77 row_ror:8 row_mask:0xf bank_mask:0xf bound_ctrl:1
	v_div_scale_f32 v85, s[4:5], v83, v83, s87
	v_div_fixup_f32 v75, v75, v84, s87
	v_mov_b32_e32 v84, v77
	v_rcp_f32_e32 v86, v85
	s_nop 0
	v_permlane16_swap_b32_e32 v77, v84
	v_add_f32_e32 v77, v77, v84
	v_fmamk_f32 v77, v77, 0x3c000000, v141
	v_mul_f32_e32 v84, 0x4f800000, v77
	v_cmp_gt_f32_e64 s[4:5], s86, v77
	v_fma_f32 v81, -v85, v86, 1.0
	v_fmac_f32_e32 v86, v81, v86
	v_cndmask_b32_e64 v77, v77, v84, s[4:5]
	v_div_scale_f32 v81, vcc, s87, v83, s87
	v_sqrt_f32_e32 v84, v77
	v_mul_f32_e32 v82, v81, v86
	v_fma_f32 v87, -v85, v82, v81
	v_fmac_f32_e32 v82, v87, v86
	v_fma_f32 v81, -v85, v82, v81
	v_add_u32_e32 v85, -1, v84
	v_fma_f32 v87, -v85, v84, v77
	v_cmp_ge_f32_e64 s[6:7], 0, v87
	v_add_u32_e32 v87, 1, v84
	v_fmac_f32_e32 v79, v42, v42
	v_cndmask_b32_e64 v85, v84, v85, s[6:7]
	v_fma_f32 v84, -v87, v84, v77
	v_fmac_f32_e32 v79, v58, v58
	v_cmp_lt_f32_e64 s[6:7], 0, v84
	v_fma_f32 v80, v9, v9, 0
	v_add_f32_dpp v79, v79, v79 quad_perm:[1,0,3,2] row_mask:0xf bank_mask:0xf bound_ctrl:1
	v_cndmask_b32_e64 v84, v85, v87, s[6:7]
	v_mul_f32_e32 v85, 0x37800000, v84
	v_add_f32_dpp v79, v79, v79 quad_perm:[2,3,0,1] row_mask:0xf bank_mask:0xf bound_ctrl:1
	v_cndmask_b32_e64 v84, v84, v85, s[4:5]
	v_cmp_class_f32_e64 s[4:5], v77, v142
	v_add_f32_dpp v79, v79, v79 row_half_mirror row_mask:0xf bank_mask:0xf bound_ctrl:1
	v_fmac_f32_e32 v80, v24, v24
	v_cndmask_b32_e64 v84, v84, v77, s[4:5]
	v_div_fmas_f32 v77, v81, v86, v82
	v_add_f32_dpp v79, v79, v79 row_ror:8 row_mask:0xf bank_mask:0xf bound_ctrl:1
	v_div_scale_f32 v85, s[4:5], v84, v84, s87
	v_div_fixup_f32 v77, v77, v83, s87
	v_mov_b32_e32 v83, v79
	v_rcp_f32_e32 v87, v85
	s_nop 0
	v_permlane16_swap_b32_e32 v79, v83
	v_add_f32_e32 v79, v79, v83
	v_fmamk_f32 v79, v79, 0x3c000000, v141
	v_mul_f32_e32 v83, 0x4f800000, v79
	v_cmp_gt_f32_e64 s[4:5], s86, v79
	v_fma_f32 v81, -v85, v87, 1.0
	v_fmac_f32_e32 v87, v81, v87
	v_cndmask_b32_e64 v79, v79, v83, s[4:5]
	v_div_scale_f32 v81, vcc, s87, v84, s87
	v_sqrt_f32_e32 v83, v79
	v_mul_f32_e32 v82, v81, v87
	v_fma_f32 v86, -v85, v82, v81
	v_fmac_f32_e32 v82, v86, v87
	v_fma_f32 v81, -v85, v82, v81
	v_add_u32_e32 v85, -1, v83
	v_fma_f32 v86, -v85, v83, v79
	v_cmp_ge_f32_e64 s[6:7], 0, v86
	v_add_u32_e32 v86, 1, v83
	v_fmac_f32_e32 v80, v40, v40
	v_cndmask_b32_e64 v85, v83, v85, s[6:7]
	v_fma_f32 v83, -v86, v83, v79
	v_fmac_f32_e32 v80, v56, v56
	v_cmp_lt_f32_e64 s[6:7], 0, v83
	v_fma_f32 v78, v7, v7, 0
	v_add_f32_dpp v80, v80, v80 quad_perm:[1,0,3,2] row_mask:0xf bank_mask:0xf bound_ctrl:1
	v_cndmask_b32_e64 v83, v85, v86, s[6:7]
	v_mul_f32_e32 v85, 0x37800000, v83
	v_add_f32_dpp v80, v80, v80 quad_perm:[2,3,0,1] row_mask:0xf bank_mask:0xf bound_ctrl:1
	v_cndmask_b32_e64 v83, v83, v85, s[4:5]
	v_cmp_class_f32_e64 s[4:5], v79, v142
	v_add_f32_dpp v80, v80, v80 row_half_mirror row_mask:0xf bank_mask:0xf bound_ctrl:1
	v_fmac_f32_e32 v78, v22, v22
	v_cndmask_b32_e64 v83, v83, v79, s[4:5]
	v_div_fmas_f32 v79, v81, v87, v82
	v_add_f32_dpp v80, v80, v80 row_ror:8 row_mask:0xf bank_mask:0xf bound_ctrl:1
	v_div_scale_f32 v85, s[4:5], v83, v83, s87
	v_div_fixup_f32 v79, v79, v84, s87
	v_mov_b32_e32 v84, v80
	v_rcp_f32_e32 v86, v85
	s_nop 0
	v_permlane16_swap_b32_e32 v80, v84
	v_add_f32_e32 v80, v80, v84
	v_fmamk_f32 v80, v80, 0x3c000000, v141
	v_mul_f32_e32 v84, 0x4f800000, v80
	v_cmp_gt_f32_e64 s[4:5], s86, v80
	v_fma_f32 v81, -v85, v86, 1.0
	v_fmac_f32_e32 v86, v81, v86
	v_cndmask_b32_e64 v80, v80, v84, s[4:5]
	v_div_scale_f32 v81, vcc, s87, v83, s87
	v_sqrt_f32_e32 v84, v80
	v_mul_f32_e32 v82, v81, v86
	v_fma_f32 v87, -v85, v82, v81
	v_fmac_f32_e32 v82, v87, v86
	v_fma_f32 v81, -v85, v82, v81
	v_add_u32_e32 v85, -1, v84
	v_fma_f32 v87, -v85, v84, v80
	v_cmp_ge_f32_e64 s[6:7], 0, v87
	v_add_u32_e32 v87, 1, v84
	v_fmac_f32_e32 v78, v38, v38
	v_cndmask_b32_e64 v85, v84, v85, s[6:7]
	v_fma_f32 v84, -v87, v84, v80
	v_fmac_f32_e32 v78, v53, v53
	v_cmp_lt_f32_e64 s[6:7], 0, v84
	v_fma_f32 v76, v13, v13, 0
	v_add_f32_dpp v78, v78, v78 quad_perm:[1,0,3,2] row_mask:0xf bank_mask:0xf bound_ctrl:1
	v_cndmask_b32_e64 v84, v85, v87, s[6:7]
	v_mul_f32_e32 v85, 0x37800000, v84
	v_add_f32_dpp v78, v78, v78 quad_perm:[2,3,0,1] row_mask:0xf bank_mask:0xf bound_ctrl:1
	v_cndmask_b32_e64 v84, v84, v85, s[4:5]
	v_cmp_class_f32_e64 s[4:5], v80, v142
	v_add_f32_dpp v78, v78, v78 row_half_mirror row_mask:0xf bank_mask:0xf bound_ctrl:1
	v_fmac_f32_e32 v76, v29, v29
	v_cndmask_b32_e64 v84, v84, v80, s[4:5]
	v_div_fmas_f32 v80, v81, v86, v82
	v_add_f32_dpp v78, v78, v78 row_ror:8 row_mask:0xf bank_mask:0xf bound_ctrl:1
	v_div_scale_f32 v85, s[4:5], v84, v84, s87
	v_div_fixup_f32 v80, v80, v83, s87
	v_mov_b32_e32 v83, v78
	v_rcp_f32_e32 v87, v85
	s_nop 0
	v_permlane16_swap_b32_e32 v78, v83
	v_add_f32_e32 v78, v78, v83
	v_fmamk_f32 v78, v78, 0x3c000000, v141
	v_mul_f32_e32 v83, 0x4f800000, v78
	v_cmp_gt_f32_e64 s[4:5], s86, v78
	v_fma_f32 v81, -v85, v87, 1.0
	v_fmac_f32_e32 v87, v81, v87
	v_cndmask_b32_e64 v78, v78, v83, s[4:5]
	v_div_scale_f32 v81, vcc, s87, v84, s87
	v_sqrt_f32_e32 v83, v78
	v_mul_f32_e32 v82, v81, v87
	v_fma_f32 v86, -v85, v82, v81
	v_fmac_f32_e32 v82, v86, v87
	v_fma_f32 v81, -v85, v82, v81
	v_add_u32_e32 v85, -1, v83
	v_fma_f32 v86, -v85, v83, v78
	v_cmp_ge_f32_e64 s[6:7], 0, v86
	v_add_u32_e32 v86, 1, v83
	v_fmac_f32_e32 v76, v45, v45
	v_cndmask_b32_e64 v85, v83, v85, s[6:7]
	v_fma_f32 v83, -v86, v83, v78
	v_fmac_f32_e32 v76, v61, v61
	v_cmp_lt_f32_e64 s[6:7], 0, v83
	v_fma_f32 v74, v11, v11, 0
	v_add_f32_dpp v76, v76, v76 quad_perm:[1,0,3,2] row_mask:0xf bank_mask:0xf bound_ctrl:1
	v_cndmask_b32_e64 v83, v85, v86, s[6:7]
	v_mul_f32_e32 v85, 0x37800000, v83
	v_add_f32_dpp v76, v76, v76 quad_perm:[2,3,0,1] row_mask:0xf bank_mask:0xf bound_ctrl:1
	v_cndmask_b32_e64 v83, v83, v85, s[4:5]
	v_cmp_class_f32_e64 s[4:5], v78, v142
	v_add_f32_dpp v76, v76, v76 row_half_mirror row_mask:0xf bank_mask:0xf bound_ctrl:1
	v_fmac_f32_e32 v74, v27, v27
	v_cndmask_b32_e64 v83, v83, v78, s[4:5]
	v_div_fmas_f32 v78, v81, v87, v82
	v_add_f32_dpp v76, v76, v76 row_ror:8 row_mask:0xf bank_mask:0xf bound_ctrl:1
	v_div_scale_f32 v85, s[4:5], v83, v83, s87
	v_div_fixup_f32 v78, v78, v84, s87
	v_mov_b32_e32 v84, v76
	v_rcp_f32_e32 v86, v85
	s_nop 0
	v_permlane16_swap_b32_e32 v76, v84
	v_add_f32_e32 v76, v76, v84
	v_fmamk_f32 v76, v76, 0x3c000000, v141
	v_mul_f32_e32 v84, 0x4f800000, v76
	v_cmp_gt_f32_e64 s[4:5], s86, v76
	v_fma_f32 v81, -v85, v86, 1.0
	v_fmac_f32_e32 v86, v81, v86
	v_cndmask_b32_e64 v76, v76, v84, s[4:5]
	v_div_scale_f32 v81, vcc, s87, v83, s87
	v_sqrt_f32_e32 v84, v76
	v_mul_f32_e32 v82, v81, v86
	v_fma_f32 v87, -v85, v82, v81
	v_fmac_f32_e32 v82, v87, v86
	v_fma_f32 v81, -v85, v82, v81
	v_add_u32_e32 v85, -1, v84
	v_fma_f32 v87, -v85, v84, v76
	v_cmp_ge_f32_e64 s[6:7], 0, v87
	v_add_u32_e32 v87, 1, v84
	v_fmac_f32_e32 v74, v43, v43
	v_cndmask_b32_e64 v85, v84, v85, s[6:7]
	v_fma_f32 v84, -v87, v84, v76
	v_fmac_f32_e32 v74, v59, v59
	v_cmp_lt_f32_e64 s[6:7], 0, v84
	v_fma_f32 v71, v8, v8, 0
	v_add_f32_dpp v74, v74, v74 quad_perm:[1,0,3,2] row_mask:0xf bank_mask:0xf bound_ctrl:1
	v_cndmask_b32_e64 v84, v85, v87, s[6:7]
	v_mul_f32_e32 v85, 0x37800000, v84
	v_add_f32_dpp v74, v74, v74 quad_perm:[2,3,0,1] row_mask:0xf bank_mask:0xf bound_ctrl:1
	v_cndmask_b32_e64 v84, v84, v85, s[4:5]
	v_cmp_class_f32_e64 s[4:5], v76, v142
	v_add_f32_dpp v74, v74, v74 row_half_mirror row_mask:0xf bank_mask:0xf bound_ctrl:1
	v_fmac_f32_e32 v71, v25, v25
	v_cndmask_b32_e64 v84, v84, v76, s[4:5]
	v_div_fmas_f32 v76, v81, v86, v82
	v_add_f32_dpp v74, v74, v74 row_ror:8 row_mask:0xf bank_mask:0xf bound_ctrl:1
	v_div_scale_f32 v85, s[4:5], v84, v84, s87
	v_div_fixup_f32 v76, v76, v83, s87
	v_mov_b32_e32 v83, v74
	v_rcp_f32_e32 v87, v85
	s_nop 0
	v_permlane16_swap_b32_e32 v74, v83
	v_add_f32_e32 v74, v74, v83
	v_fmamk_f32 v74, v74, 0x3c000000, v141
	v_mul_f32_e32 v83, 0x4f800000, v74
	v_cmp_gt_f32_e64 s[4:5], s86, v74
	v_fma_f32 v81, -v85, v87, 1.0
	v_fmac_f32_e32 v87, v81, v87
	v_cndmask_b32_e64 v74, v74, v83, s[4:5]
	v_div_scale_f32 v81, vcc, s87, v84, s87
	v_sqrt_f32_e32 v83, v74
	v_mul_f32_e32 v82, v81, v87
	v_fma_f32 v86, -v85, v82, v81
	v_fmac_f32_e32 v82, v86, v87
	v_fma_f32 v81, -v85, v82, v81
	v_add_u32_e32 v85, -1, v83
	v_fma_f32 v86, -v85, v83, v74
	v_cmp_ge_f32_e64 s[6:7], 0, v86
	v_add_u32_e32 v86, 1, v83
	v_fmac_f32_e32 v71, v41, v41
	v_cndmask_b32_e64 v85, v83, v85, s[6:7]
	v_fma_f32 v83, -v86, v83, v74
	v_fmac_f32_e32 v71, v57, v57
	v_cmp_lt_f32_e64 s[6:7], 0, v83
	v_fma_f32 v70, v6, v6, 0
	v_add_f32_dpp v71, v71, v71 quad_perm:[1,0,3,2] row_mask:0xf bank_mask:0xf bound_ctrl:1
	v_cndmask_b32_e64 v83, v85, v86, s[6:7]
	v_mul_f32_e32 v85, 0x37800000, v83
	v_add_f32_dpp v71, v71, v71 quad_perm:[2,3,0,1] row_mask:0xf bank_mask:0xf bound_ctrl:1
	v_cndmask_b32_e64 v83, v83, v85, s[4:5]
	v_cmp_class_f32_e64 s[4:5], v74, v142
	v_add_f32_dpp v71, v71, v71 row_half_mirror row_mask:0xf bank_mask:0xf bound_ctrl:1
	v_fmac_f32_e32 v70, v23, v23
	v_cndmask_b32_e64 v83, v83, v74, s[4:5]
	v_div_fmas_f32 v74, v81, v87, v82
	v_add_f32_dpp v71, v71, v71 row_ror:8 row_mask:0xf bank_mask:0xf bound_ctrl:1
	v_div_scale_f32 v85, s[4:5], v83, v83, s87
	v_div_fixup_f32 v74, v74, v84, s87
	v_mov_b32_e32 v84, v71
	v_rcp_f32_e32 v86, v85
	s_nop 0
	v_permlane16_swap_b32_e32 v71, v84
	v_add_f32_e32 v71, v71, v84
	v_fmamk_f32 v71, v71, 0x3c000000, v141
	v_mul_f32_e32 v84, 0x4f800000, v71
	v_cmp_gt_f32_e64 s[4:5], s86, v71
	v_fma_f32 v81, -v85, v86, 1.0
	v_fmac_f32_e32 v86, v81, v86
	v_cndmask_b32_e64 v71, v71, v84, s[4:5]
	v_div_scale_f32 v81, vcc, s87, v83, s87
	v_sqrt_f32_e32 v84, v71
	v_mul_f32_e32 v82, v81, v86
	v_fma_f32 v87, -v85, v82, v81
	v_fmac_f32_e32 v82, v87, v86
	v_fma_f32 v81, -v85, v82, v81
	v_add_u32_e32 v85, -1, v84
	v_fma_f32 v87, -v85, v84, v71
	v_cmp_ge_f32_e64 s[6:7], 0, v87
	v_add_u32_e32 v87, 1, v84
	v_fmac_f32_e32 v70, v39, v39
	v_cndmask_b32_e64 v85, v84, v85, s[6:7]
	v_fma_f32 v84, -v87, v84, v71
	v_fmac_f32_e32 v70, v54, v54
	v_cmp_lt_f32_e64 s[6:7], 0, v84
	v_fma_f32 v69, v5, v5, 0
	v_add_f32_dpp v70, v70, v70 quad_perm:[1,0,3,2] row_mask:0xf bank_mask:0xf bound_ctrl:1
	v_cndmask_b32_e64 v84, v85, v87, s[6:7]
	v_mul_f32_e32 v85, 0x37800000, v84
	v_add_f32_dpp v70, v70, v70 quad_perm:[2,3,0,1] row_mask:0xf bank_mask:0xf bound_ctrl:1
	v_cndmask_b32_e64 v84, v84, v85, s[4:5]
	v_cmp_class_f32_e64 s[4:5], v71, v142
	v_add_f32_dpp v70, v70, v70 row_half_mirror row_mask:0xf bank_mask:0xf bound_ctrl:1
	v_fmac_f32_e32 v69, v21, v21
	v_cndmask_b32_e64 v84, v84, v71, s[4:5]
	v_div_fmas_f32 v71, v81, v86, v82
	v_add_f32_dpp v70, v70, v70 row_ror:8 row_mask:0xf bank_mask:0xf bound_ctrl:1
	v_div_scale_f32 v85, s[4:5], v84, v84, s87
	v_div_fixup_f32 v71, v71, v83, s87
	v_mov_b32_e32 v83, v70
	v_rcp_f32_e32 v87, v85
	s_nop 0
	v_permlane16_swap_b32_e32 v70, v83
	v_add_f32_e32 v70, v70, v83
	v_fmamk_f32 v70, v70, 0x3c000000, v141
	v_mul_f32_e32 v83, 0x4f800000, v70
	v_cmp_gt_f32_e64 s[4:5], s86, v70
	v_fma_f32 v81, -v85, v87, 1.0
	v_fmac_f32_e32 v87, v81, v87
	v_cndmask_b32_e64 v70, v70, v83, s[4:5]
	v_div_scale_f32 v81, vcc, s87, v84, s87
	v_sqrt_f32_e32 v83, v70
	v_mul_f32_e32 v82, v81, v87
	v_fma_f32 v86, -v85, v82, v81
	v_fmac_f32_e32 v82, v86, v87
	v_fma_f32 v81, -v85, v82, v81
	v_add_u32_e32 v85, -1, v83
	v_fma_f32 v86, -v85, v83, v70
	v_cmp_ge_f32_e64 s[6:7], 0, v86
	v_add_u32_e32 v86, 1, v83
	v_fmac_f32_e32 v69, v37, v37
	v_cndmask_b32_e64 v85, v83, v85, s[6:7]
	v_fma_f32 v83, -v86, v83, v70
	v_fmac_f32_e32 v69, v50, v50
	v_cmp_lt_f32_e64 s[6:7], 0, v83
	v_fma_f32 v68, v4, v4, 0
	v_add_f32_dpp v69, v69, v69 quad_perm:[1,0,3,2] row_mask:0xf bank_mask:0xf bound_ctrl:1
	v_cndmask_b32_e64 v83, v85, v86, s[6:7]
	v_mul_f32_e32 v85, 0x37800000, v83
	v_add_f32_dpp v69, v69, v69 quad_perm:[2,3,0,1] row_mask:0xf bank_mask:0xf bound_ctrl:1
	v_cndmask_b32_e64 v83, v83, v85, s[4:5]
	v_cmp_class_f32_e64 s[4:5], v70, v142
	v_add_f32_dpp v69, v69, v69 row_half_mirror row_mask:0xf bank_mask:0xf bound_ctrl:1
	v_fmac_f32_e32 v68, v20, v20
	v_cndmask_b32_e64 v83, v83, v70, s[4:5]
	v_div_fmas_f32 v70, v81, v87, v82
	v_add_f32_dpp v69, v69, v69 row_ror:8 row_mask:0xf bank_mask:0xf bound_ctrl:1
	v_div_scale_f32 v85, s[4:5], v83, v83, s87
	v_div_fixup_f32 v70, v70, v84, s87
	v_mov_b32_e32 v84, v69
	v_rcp_f32_e32 v86, v85
	s_nop 0
	v_permlane16_swap_b32_e32 v69, v84
	v_add_f32_e32 v69, v69, v84
	v_fmamk_f32 v69, v69, 0x3c000000, v141
	v_mul_f32_e32 v84, 0x4f800000, v69
	v_cmp_gt_f32_e64 s[4:5], s86, v69
	v_fma_f32 v81, -v85, v86, 1.0
	v_fmac_f32_e32 v86, v81, v86
	v_cndmask_b32_e64 v69, v69, v84, s[4:5]
	v_div_scale_f32 v81, vcc, s87, v83, s87
	v_sqrt_f32_e32 v84, v69
	v_mul_f32_e32 v82, v81, v86
	v_fma_f32 v87, -v85, v82, v81
	v_fmac_f32_e32 v82, v87, v86
	v_fma_f32 v81, -v85, v82, v81
	v_add_u32_e32 v85, -1, v84
	v_fma_f32 v87, -v85, v84, v69
	v_cmp_ge_f32_e64 s[6:7], 0, v87
	v_add_u32_e32 v87, 1, v84
	v_fmac_f32_e32 v68, v36, v36
	v_cndmask_b32_e64 v85, v84, v85, s[6:7]
	v_fma_f32 v84, -v87, v84, v69
	v_fmac_f32_e32 v68, v55, v55
	v_cmp_lt_f32_e64 s[6:7], 0, v84
	v_fma_f32 v1, v3, v3, 0
	v_add_f32_dpp v68, v68, v68 quad_perm:[1,0,3,2] row_mask:0xf bank_mask:0xf bound_ctrl:1
	v_cndmask_b32_e64 v84, v85, v87, s[6:7]
	v_mul_f32_e32 v85, 0x37800000, v84
	v_add_f32_dpp v68, v68, v68 quad_perm:[2,3,0,1] row_mask:0xf bank_mask:0xf bound_ctrl:1
	v_cndmask_b32_e64 v84, v84, v85, s[4:5]
	v_cmp_class_f32_e64 s[4:5], v69, v142
	v_add_f32_dpp v68, v68, v68 row_half_mirror row_mask:0xf bank_mask:0xf bound_ctrl:1
	v_fmac_f32_e32 v1, v19, v19
	v_cndmask_b32_e64 v84, v84, v69, s[4:5]
	v_div_fmas_f32 v69, v81, v86, v82
	v_add_f32_dpp v68, v68, v68 row_ror:8 row_mask:0xf bank_mask:0xf bound_ctrl:1
	v_div_scale_f32 v85, s[4:5], v84, v84, s87
	v_div_fixup_f32 v69, v69, v83, s87
	v_mov_b32_e32 v83, v68
	v_rcp_f32_e32 v87, v85
	s_nop 0
	v_permlane16_swap_b32_e32 v68, v83
	v_add_f32_e32 v68, v68, v83
	v_fmamk_f32 v68, v68, 0x3c000000, v141
	v_mul_f32_e32 v83, 0x4f800000, v68
	v_cmp_gt_f32_e64 s[4:5], s86, v68
	v_fma_f32 v81, -v85, v87, 1.0
	v_fmac_f32_e32 v87, v81, v87
	v_cndmask_b32_e64 v68, v68, v83, s[4:5]
	v_div_scale_f32 v81, vcc, s87, v84, s87
	v_sqrt_f32_e32 v83, v68
	v_mul_f32_e32 v82, v81, v87
	v_fma_f32 v86, -v85, v82, v81
	v_fmac_f32_e32 v82, v86, v87
	v_fma_f32 v81, -v85, v82, v81
	v_add_u32_e32 v85, -1, v83
	v_fma_f32 v86, -v85, v83, v68
	v_cmp_ge_f32_e64 s[6:7], 0, v86
	v_add_u32_e32 v86, 1, v83
	v_fmac_f32_e32 v1, v35, v35
	v_cndmask_b32_e64 v85, v83, v85, s[6:7]
	v_fma_f32 v83, -v86, v83, v68
	v_cmp_lt_f32_e64 s[6:7], 0, v83
	v_fmac_f32_e32 v1, v51, v51
	v_lshlrev_b32_e32 v89, 2, v64
	v_cndmask_b32_e64 v83, v85, v86, s[6:7]
	v_mul_f32_e32 v85, 0x37800000, v83
	v_add_f32_dpp v1, v1, v1 quad_perm:[1,0,3,2] row_mask:0xf bank_mask:0xf bound_ctrl:1
	v_cndmask_b32_e64 v83, v83, v85, s[4:5]
	v_cmp_class_f32_e64 s[4:5], v68, v142
	v_add_f32_dpp v1, v1, v1 quad_perm:[2,3,0,1] row_mask:0xf bank_mask:0xf bound_ctrl:1
	v_fma_f32 v0, v2, v2, 0
	v_cndmask_b32_e64 v85, v83, v68, s[4:5]
	v_add_f32_dpp v1, v1, v1 row_half_mirror row_mask:0xf bank_mask:0xf bound_ctrl:1
	v_div_scale_f32 v83, s[4:5], v85, v85, s87
	s_nop 0
	v_add_f32_dpp v1, v1, v1 row_ror:8 row_mask:0xf bank_mask:0xf bound_ctrl:1
	v_rcp_f32_e32 v86, v83
	v_div_fmas_f32 v68, v81, v87, v82
	v_mov_b32_e32 v82, v1
	s_nop 1
	v_permlane16_swap_b32_e32 v1, v82
	v_add_f32_e32 v1, v1, v82
	v_fmamk_f32 v1, v1, 0x3c000000, v141
	v_fma_f32 v81, -v83, v86, 1.0
	v_mul_f32_e32 v82, 0x4f800000, v1
	v_cmp_gt_f32_e64 s[4:5], s86, v1
	v_fmac_f32_e32 v86, v81, v86
	v_div_scale_f32 v81, vcc, s87, v85, s87
	v_cndmask_b32_e64 v1, v1, v82, s[4:5]
	v_mul_f32_e32 v87, v81, v86
	v_sqrt_f32_e32 v82, v1
	v_div_fixup_f32 v68, v68, v84, s87
	v_fma_f32 v84, -v83, v87, v81
	v_fmac_f32_e32 v87, v84, v86
	v_fma_f32 v88, -v83, v87, v81
	global_load_dword v81, v89, s[8:9]
	v_add_u32_e32 v83, -1, v82
	v_fma_f32 v84, -v83, v82, v1
	v_cmp_ge_f32_e64 s[6:7], 0, v84
	v_add_u32_e32 v84, 1, v82
	v_fma_f32 v90, -v84, v82, v1
	v_cndmask_b32_e64 v83, v82, v83, s[6:7]
	global_load_dword v82, v89, s[8:9] offset:128
	v_cmp_lt_f32_e64 s[6:7], 0, v90
	v_fmac_f32_e32 v0, v18, v18
	v_fmac_f32_e32 v0, v34, v34
	v_cndmask_b32_e64 v83, v83, v84, s[6:7]
	v_mul_f32_e32 v84, 0x37800000, v83
	v_cndmask_b32_e64 v84, v83, v84, s[4:5]
	global_load_dword v83, v89, s[8:9] offset:256
	v_cmp_class_f32_e64 s[4:5], v1, v142
	v_fma_f32 v52, -v140, v95, v52
	v_fmac_f32_e32 v0, v52, v52
	v_cndmask_b32_e64 v1, v84, v1, s[4:5]
	global_load_dword v84, v89, s[8:9] offset:384
	v_add_f32_dpp v0, v0, v0 quad_perm:[1,0,3,2] row_mask:0xf bank_mask:0xf bound_ctrl:1
	v_div_scale_f32 v90, s[4:5], v1, v1, s87
	s_nop 0
	v_add_f32_dpp v0, v0, v0 quad_perm:[2,3,0,1] row_mask:0xf bank_mask:0xf bound_ctrl:1
	v_div_fmas_f32 v86, v88, v86, v87
	v_rcp_f32_e32 v89, v90
	v_add_f32_dpp v0, v0, v0 row_half_mirror row_mask:0xf bank_mask:0xf bound_ctrl:1
	v_div_fixup_f32 v85, v86, v85, s87
	v_mov_b32_e32 v133, v128
	v_add_f32_dpp v0, v0, v0 row_ror:8 row_mask:0xf bank_mask:0xf bound_ctrl:1
	v_mov_b32_e32 v88, v0
	s_nop 1
	v_permlane16_swap_b32_e32 v0, v88
	v_add_f32_e32 v0, v0, v88
	v_fmamk_f32 v0, v0, 0x3c000000, v141
	v_mul_f32_e32 v88, 0x4f800000, v0
	v_cmp_gt_f32_e64 s[4:5], s86, v0
	v_fma_f32 v86, -v90, v89, 1.0
	v_fmac_f32_e32 v89, v86, v89
	v_cndmask_b32_e64 v0, v0, v88, s[4:5]
	v_div_scale_f32 v86, vcc, s87, v1, s87
	v_sqrt_f32_e32 v88, v0
	v_mul_f32_e32 v87, v86, v89
	v_fma_f32 v91, -v90, v87, v86
	v_fmac_f32_e32 v87, v91, v89
	v_fma_f32 v86, -v90, v87, v86
	v_add_u32_e32 v90, -1, v88
	v_fma_f32 v91, -v90, v88, v0
	v_cmp_ge_f32_e64 s[6:7], 0, v91
	v_add_u32_e32 v91, 1, v88
	v_div_fmas_f32 v86, v86, v89, v87
	v_cndmask_b32_e64 v90, v88, v90, s[6:7]
	v_fma_f32 v88, -v91, v88, v0
	v_cmp_lt_f32_e64 s[6:7], 0, v88
	v_div_fixup_f32 v87, v86, v1, s87
	v_mul_f32_e32 v17, v17, v72
	v_cndmask_b32_e64 v88, v90, v91, s[6:7]
	v_mul_f32_e32 v90, 0x37800000, v88
	v_cndmask_b32_e64 v88, v88, v90, s[4:5]
	v_cmp_class_f32_e64 s[4:5], v0, v142
	v_lshlrev_b32_e32 v64, 1, v64
	v_mul_f32_e32 v16, v16, v73
	v_cndmask_b32_e64 v0, v88, v0, s[4:5]
	v_div_scale_f32 v88, s[4:5], v0, v0, s87
	v_rcp_f32_e32 v90, v88
	v_mul_f32_e32 v15, v15, v75
	v_mul_f32_e32 v14, v14, v77
	v_mul_f32_e32 v12, v12, v79
	v_fma_f32 v1, -v88, v90, 1.0
	v_fmac_f32_e32 v90, v1, v90
	v_div_scale_f32 v1, vcc, s87, v0, s87
	v_mul_f32_e32 v86, v1, v90
	v_fma_f32 v89, -v88, v86, v1
	v_fmac_f32_e32 v86, v89, v90
	v_fma_f32 v1, -v88, v86, v1
	v_div_fmas_f32 v1, v1, v90, v86
	v_lshlrev_b32_e32 v88, 2, v65
	v_div_fixup_f32 v86, v1, v0, s87
	v_lshl_add_u64 v[0:1], s[66:67], 0, v[132:133]
	v_mov_b32_e32 v65, v128
	v_ashrrev_i32_e32 v89, 31, v88
	s_waitcnt vmcnt(3)
	v_mul_f32_e32 v17, v17, v81
	v_lshl_add_u64 v[64:65], v[0:1], 0, v[64:65]
	v_mbcnt_lo_u32_b32 v236, -1, 0
	v_mbcnt_hi_u32_b32 v236, -1, v236
	v_and_b32_e32 v237, 31, v236
	v_lshrrev_b32_e32 v238, 5, v236
	v_lshlrev_b32_e32 v239, 1, v237
	v_lshl_add_u32 v240, v238, 10, v239
	v_mov_b32_e32 v238, s93
	v_lshlrev_b32_e32 v238, 13, v238
	v_add_u32_e32 v238, 0x18000, v238
	v_add_u32_e32 v240, v240, v238
	v_lshl_add_u32 v241, v236, 4, v238
	v_lshrrev_b32_e32 v237, 4, v236
	v_and_b32_e32 v236, 15, v236
	v_lshlrev_b32_e32 v237, 11, v237
	v_lshl_add_u32 v237, v236, 4, v237
	v_sub_u32_e32 v236, v237, v239
	v_ashrrev_i32_e32 v237, 31, v236
	v_lshl_add_u64 v[242:243], v[64:65], 0, v[236:237]
	v_mov_b32_e32 v232, 0x2000
	v_mov_b32_e32 v233, 0
	v_lshlrev_b64 v[0:1], 11, v[88:89]
	v_bfe_u32 v89, v17, 16, 1
	v_lshl_add_u64 v[0:1], v[64:65], 0, v[0:1]
	v_add3_u32 v17, v17, v89, s88
	ds_write_b16_d16_hi v240, v17
	v_mul_f32_e32 v17, v33, v72
	s_waitcnt vmcnt(2)
	v_mul_f32_e32 v17, v17, v82
	v_bfe_u32 v33, v17, 16, 1
	v_add3_u32 v17, v17, v33, s88
	ds_write_b16_d16_hi v240, v17 offset:64
	v_mul_f32_e32 v17, v49, v72
	s_waitcnt vmcnt(1)
	v_mul_f32_e32 v17, v17, v83
	v_bfe_u32 v33, v17, 16, 1
	v_add3_u32 v17, v17, v33, s88
	ds_write_b16_d16_hi v240, v17 offset:128
	v_mul_f32_e32 v17, v67, v72
	s_waitcnt vmcnt(0)
	v_mul_f32_e32 v17, v17, v84
	v_bfe_u32 v33, v17, 16, 1
	v_or_b32_e32 v90, 1, v88
	v_add3_u32 v17, v17, v33, s88
	v_ashrrev_i32_e32 v91, 31, v90
	v_mul_f32_e32 v16, v16, v81
	ds_write_b16_d16_hi v240, v17 offset:192
	v_lshlrev_b64 v[90:91], 11, v[90:91]
	v_bfe_u32 v17, v16, 16, 1
	v_lshl_add_u64 v[90:91], v[64:65], 0, v[90:91]
	v_add3_u32 v16, v16, v17, s88
	ds_write_b16_d16_hi v240, v16 offset:256
	v_mul_f32_e32 v16, v32, v73
	v_mul_f32_e32 v16, v16, v82
	v_bfe_u32 v17, v16, 16, 1
	v_add3_u32 v16, v16, v17, s88
	ds_write_b16_d16_hi v240, v16 offset:320
	v_mul_f32_e32 v16, v48, v73
	v_mul_f32_e32 v16, v16, v83
	v_bfe_u32 v17, v16, 16, 1
	v_add3_u32 v16, v16, v17, s88
	ds_write_b16_d16_hi v240, v16 offset:384
	v_mul_f32_e32 v16, v66, v73
	v_mul_f32_e32 v16, v16, v84
	v_bfe_u32 v17, v16, 16, 1
	v_add3_u32 v16, v16, v17, s88
	ds_write_b16_d16_hi v240, v16 offset:448
	v_or_b32_e32 v16, 2, v88
	v_ashrrev_i32_e32 v17, 31, v16
	v_mul_f32_e32 v15, v15, v81
	v_lshlrev_b64 v[16:17], 11, v[16:17]
	v_bfe_u32 v32, v15, 16, 1
	v_lshl_add_u64 v[16:17], v[64:65], 0, v[16:17]
	v_add3_u32 v15, v15, v32, s88
	ds_write_b16_d16_hi v240, v15 offset:512
	v_mul_f32_e32 v15, v31, v75
	v_mul_f32_e32 v15, v15, v82
	v_bfe_u32 v31, v15, 16, 1
	v_add3_u32 v15, v15, v31, s88
	ds_write_b16_d16_hi v240, v15 offset:576
	v_mul_f32_e32 v15, v47, v75
	v_mul_f32_e32 v15, v15, v83
	v_bfe_u32 v31, v15, 16, 1
	v_add3_u32 v15, v15, v31, s88
	ds_write_b16_d16_hi v240, v15 offset:640
	v_mul_f32_e32 v15, v63, v75
	v_mul_f32_e32 v15, v15, v84
	v_bfe_u32 v31, v15, 16, 1
	v_add3_u32 v15, v15, v31, s88
	ds_write_b16_d16_hi v240, v15 offset:704
	v_or_b32_e32 v16, 3, v88
	v_ashrrev_i32_e32 v17, 31, v16
	v_mul_f32_e32 v14, v14, v81
	v_lshlrev_b64 v[16:17], 11, v[16:17]
	v_bfe_u32 v15, v14, 16, 1
	v_lshl_add_u64 v[16:17], v[64:65], 0, v[16:17]
	v_add3_u32 v14, v14, v15, s88
	ds_write_b16_d16_hi v240, v14 offset:768
	v_mul_f32_e32 v14, v30, v77
	v_mul_f32_e32 v14, v14, v82
	v_bfe_u32 v15, v14, 16, 1
	v_add3_u32 v14, v14, v15, s88
	ds_write_b16_d16_hi v240, v14 offset:832
	v_mul_f32_e32 v14, v46, v77
	v_mul_f32_e32 v14, v14, v83
	v_bfe_u32 v15, v14, 16, 1
	v_add3_u32 v14, v14, v15, s88
	ds_write_b16_d16_hi v240, v14 offset:896
	v_mul_f32_e32 v14, v62, v77
	v_mul_f32_e32 v14, v14, v84
	v_bfe_u32 v15, v14, 16, 1
	v_add3_u32 v14, v14, v15, s88
	s_mov_b64 s[4:5], 0x4000
	v_mul_f32_e32 v12, v12, v81
	ds_write_b16_d16_hi v240, v14 offset:960
	v_lshl_add_u64 v[14:15], v[0:1], 0, s[4:5]
	v_bfe_u32 v16, v12, 16, 1
	s_movk_i32 s4, 0x4000
	v_add3_u32 v12, v12, v16, s88
	v_add_co_u32_e32 v16, vcc, s4, v0
	s_movk_i32 s4, 0x5000
	s_nop 0
	v_addc_co_u32_e32 v17, vcc, 0, v1, vcc
	v_add_co_u32_e32 v30, vcc, s4, v0
	v_mul_f32_e32 v10, v10, v80
	s_nop 0
	v_addc_co_u32_e32 v31, vcc, 0, v1, vcc
	ds_write_b16_d16_hi v240, v12 offset:2048
	v_mul_f32_e32 v12, v28, v79
	v_mul_f32_e32 v12, v12, v82
	v_bfe_u32 v28, v12, 16, 1
	v_add3_u32 v12, v12, v28, s88
	ds_write_b16_d16_hi v240, v12 offset:2112
	v_mul_f32_e32 v12, v44, v79
	v_mul_f32_e32 v12, v12, v83
	v_bfe_u32 v28, v12, 16, 1
	v_add3_u32 v12, v12, v28, s88
	ds_write_b16_d16_hi v240, v12 offset:2176
	v_mul_f32_e32 v12, v60, v79
	v_mul_f32_e32 v12, v12, v84
	v_bfe_u32 v28, v12, 16, 1
	v_add3_u32 v12, v12, v28, s88
	v_mul_f32_e32 v10, v10, v81
	ds_write_b16_d16_hi v240, v12 offset:2240
	v_bfe_u32 v12, v10, 16, 1
	v_add3_u32 v10, v10, v12, s88
	ds_write_b16_d16_hi v240, v10 offset:2304
	v_mul_f32_e32 v10, v26, v80
	v_mul_f32_e32 v10, v10, v82
	s_mov_b64 s[4:5], 0x4800
	v_bfe_u32 v12, v10, 16, 1
	v_lshl_add_u64 v[14:15], v[0:1], 0, s[4:5]
	v_add3_u32 v10, v10, v12, s88
	ds_write_b16_d16_hi v240, v10 offset:2368
	v_mul_f32_e32 v10, v42, v80
	v_mul_f32_e32 v10, v10, v83
	v_bfe_u32 v12, v10, 16, 1
	v_add3_u32 v10, v10, v12, s88
	ds_write_b16_d16_hi v240, v10 offset:2432
	v_mul_f32_e32 v10, v58, v80
	v_mul_f32_e32 v10, v10, v84
	v_bfe_u32 v12, v10, 16, 1
	v_mul_f32_e32 v9, v9, v78
	v_add3_u32 v10, v10, v12, s88
	v_mul_f32_e32 v9, v9, v81
	ds_write_b16_d16_hi v240, v10 offset:2496
	v_bfe_u32 v10, v9, 16, 1
	v_add3_u32 v9, v9, v10, s88
	ds_write_b16_d16_hi v240, v9 offset:2560
	v_mul_f32_e32 v9, v24, v78
	v_mul_f32_e32 v9, v9, v82
	s_mov_b64 s[4:5], 0x5000
	v_bfe_u32 v10, v9, 16, 1
	v_lshl_add_u64 v[14:15], v[0:1], 0, s[4:5]
	v_add3_u32 v9, v9, v10, s88
	ds_write_b16_d16_hi v240, v9 offset:2624
	v_mul_f32_e32 v9, v40, v78
	v_mul_f32_e32 v9, v9, v83
	v_bfe_u32 v10, v9, 16, 1
	v_add3_u32 v9, v9, v10, s88
	ds_write_b16_d16_hi v240, v9 offset:2688
	v_mul_f32_e32 v9, v56, v78
	v_mul_f32_e32 v9, v9, v84
	v_bfe_u32 v10, v9, 16, 1
	v_mul_f32_e32 v7, v7, v76
	v_add3_u32 v9, v9, v10, s88
	v_mul_f32_e32 v7, v7, v81
	ds_write_b16_d16_hi v240, v9 offset:2752
	v_bfe_u32 v9, v7, 16, 1
	v_add3_u32 v7, v7, v9, s88
	ds_write_b16_d16_hi v240, v7 offset:2816
	v_mul_f32_e32 v7, v22, v76
	v_mul_f32_e32 v7, v7, v82
	s_mov_b64 s[4:5], 0x5800
	v_bfe_u32 v9, v7, 16, 1
	v_lshl_add_u64 v[14:15], v[0:1], 0, s[4:5]
	v_add3_u32 v7, v7, v9, s88
	ds_write_b16_d16_hi v240, v7 offset:2880
	v_mul_f32_e32 v7, v38, v76
	v_mul_f32_e32 v7, v7, v83
	v_bfe_u32 v9, v7, 16, 1
	v_add3_u32 v7, v7, v9, s88
	ds_write_b16_d16_hi v240, v7 offset:2944
	v_mul_f32_e32 v7, v53, v76
	v_mul_f32_e32 v7, v7, v84
	v_bfe_u32 v9, v7, 16, 1
	v_add3_u32 v7, v7, v9, s88
	s_mov_b64 s[4:5], 0x8000
	ds_write_b16_d16_hi v240, v7 offset:3008
	v_lshl_add_u64 v[14:15], v[0:1], 0, s[4:5]
	s_mov_b32 s4, 0x8000
	v_mul_f32_e32 v7, v13, v74
	v_add_co_u32_e32 v12, vcc, s4, v0
	v_mul_f32_e32 v7, v7, v81
	s_nop 0
	v_addc_co_u32_e32 v13, vcc, 0, v1, vcc
	s_mov_b32 s4, 0x9000
	v_bfe_u32 v9, v7, 16, 1
	v_add_co_u32_e32 v16, vcc, s4, v0
	v_add3_u32 v7, v7, v9, s88
	s_nop 0
	v_addc_co_u32_e32 v17, vcc, 0, v1, vcc
	ds_write_b16_d16_hi v240, v7 offset:4096
	v_mul_f32_e32 v7, v29, v74
	v_mul_f32_e32 v7, v7, v82
	v_bfe_u32 v9, v7, 16, 1
	v_add3_u32 v7, v7, v9, s88
	ds_write_b16_d16_hi v240, v7 offset:4160
	v_mul_f32_e32 v7, v45, v74
	v_mul_f32_e32 v7, v7, v83
	v_bfe_u32 v9, v7, 16, 1
	v_add3_u32 v7, v7, v9, s88
	ds_write_b16_d16_hi v240, v7 offset:4224
	v_mul_f32_e32 v7, v61, v74
	v_mul_f32_e32 v7, v7, v84
	v_bfe_u32 v9, v7, 16, 1
	v_add3_u32 v7, v7, v9, s88
	ds_write_b16_d16_hi v240, v7 offset:4288
	v_mul_f32_e32 v7, v11, v71
	v_mul_f32_e32 v7, v7, v81
	v_bfe_u32 v9, v7, 16, 1
	v_add3_u32 v7, v7, v9, s88
	ds_write_b16_d16_hi v240, v7 offset:4352
	v_mul_f32_e32 v7, v27, v71
	v_mul_f32_e32 v7, v7, v82
	s_mov_b64 s[4:5], 0x8800
	v_bfe_u32 v9, v7, 16, 1
	v_lshl_add_u64 v[14:15], v[0:1], 0, s[4:5]
	v_add3_u32 v7, v7, v9, s88
	ds_write_b16_d16_hi v240, v7 offset:4416
	v_mul_f32_e32 v7, v43, v71
	v_mul_f32_e32 v7, v7, v83
	v_bfe_u32 v9, v7, 16, 1
	v_add3_u32 v7, v7, v9, s88
	ds_write_b16_d16_hi v240, v7 offset:4480
	v_mul_f32_e32 v7, v59, v71
	v_mul_f32_e32 v7, v7, v84
	v_bfe_u32 v9, v7, 16, 1
	v_add3_u32 v7, v7, v9, s88
	ds_write_b16_d16_hi v240, v7 offset:4544
	v_mul_f32_e32 v7, v8, v70
	v_mul_f32_e32 v7, v7, v81
	v_bfe_u32 v8, v7, 16, 1
	v_add3_u32 v7, v7, v8, s88
	ds_write_b16_d16_hi v240, v7 offset:4608
	v_mul_f32_e32 v7, v25, v70
	v_mul_f32_e32 v7, v7, v82
	s_mov_b64 s[4:5], 0x9000
	v_bfe_u32 v8, v7, 16, 1
	v_lshl_add_u64 v[10:11], v[0:1], 0, s[4:5]
	v_add3_u32 v7, v7, v8, s88
	ds_write_b16_d16_hi v240, v7 offset:4672
	v_mul_f32_e32 v7, v41, v70
	v_mul_f32_e32 v7, v7, v83
	v_bfe_u32 v8, v7, 16, 1
	v_add3_u32 v7, v7, v8, s88
	ds_write_b16_d16_hi v240, v7 offset:4736
	v_mul_f32_e32 v7, v57, v70
	v_mul_f32_e32 v7, v7, v84
	v_bfe_u32 v8, v7, 16, 1
	v_mul_f32_e32 v6, v6, v69
	v_add3_u32 v7, v7, v8, s88
	v_mul_f32_e32 v6, v6, v81
	ds_write_b16_d16_hi v240, v7 offset:4800
	v_bfe_u32 v7, v6, 16, 1
	v_add3_u32 v6, v6, v7, s88
	ds_write_b16_d16_hi v240, v6 offset:4864
	v_mul_f32_e32 v6, v23, v69
	v_mul_f32_e32 v6, v6, v82
	s_mov_b64 s[4:5], 0x9800
	v_bfe_u32 v7, v6, 16, 1
	v_lshl_add_u64 v[8:9], v[0:1], 0, s[4:5]
	v_add3_u32 v6, v6, v7, s88
	ds_write_b16_d16_hi v240, v6 offset:4928
	v_mul_f32_e32 v6, v39, v69
	v_mul_f32_e32 v6, v6, v83
	v_bfe_u32 v7, v6, 16, 1
	v_add3_u32 v6, v6, v7, s88
	ds_write_b16_d16_hi v240, v6 offset:4992
	v_mul_f32_e32 v6, v54, v69
	v_mul_f32_e32 v6, v6, v84
	v_bfe_u32 v7, v6, 16, 1
	v_mul_f32_e32 v5, v5, v68
	v_add3_u32 v6, v6, v7, s88
	s_mov_b64 s[4:5], 0xc000
	v_mul_f32_e32 v5, v5, v81
	ds_write_b16_d16_hi v240, v6 offset:5056
	v_lshl_add_u64 v[6:7], v[0:1], 0, s[4:5]
	v_bfe_u32 v8, v5, 16, 1
	s_mov_b32 s4, 0xc000
	v_add3_u32 v5, v5, v8, s88
	v_add_co_u32_e32 v8, vcc, s4, v0
	v_mul_f32_e32 v4, v4, v85
	s_nop 0
	v_addc_co_u32_e32 v9, vcc, 0, v1, vcc
	v_add_co_u32_e32 v10, vcc, s89, v0
	v_mul_f32_e32 v4, v4, v81
	s_nop 0
	v_addc_co_u32_e32 v11, vcc, 0, v1, vcc
	ds_write_b16_d16_hi v240, v5 offset:6144
	v_mul_f32_e32 v5, v21, v68
	v_mul_f32_e32 v5, v5, v82
	v_bfe_u32 v12, v5, 16, 1
	v_add3_u32 v5, v5, v12, s88
	ds_write_b16_d16_hi v240, v5 offset:6208
	v_mul_f32_e32 v5, v37, v68
	v_mul_f32_e32 v5, v5, v83
	v_bfe_u32 v12, v5, 16, 1
	v_add3_u32 v5, v5, v12, s88
	ds_write_b16_d16_hi v240, v5 offset:6272
	v_mul_f32_e32 v5, v50, v68
	v_mul_f32_e32 v5, v5, v84
	v_bfe_u32 v12, v5, 16, 1
	v_add3_u32 v5, v5, v12, s88
	ds_write_b16_d16_hi v240, v5 offset:6336
	v_bfe_u32 v5, v4, 16, 1
	v_add3_u32 v4, v4, v5, s88
	ds_write_b16_d16_hi v240, v4 offset:6400
	v_mul_f32_e32 v4, v20, v85
	v_mul_f32_e32 v4, v4, v82
	s_mov_b64 s[4:5], 0xc800
	v_bfe_u32 v5, v4, 16, 1
	v_lshl_add_u64 v[6:7], v[0:1], 0, s[4:5]
	v_add3_u32 v4, v4, v5, s88
	ds_write_b16_d16_hi v240, v4 offset:6464
	v_mul_f32_e32 v4, v36, v85
	v_mul_f32_e32 v4, v4, v83
	v_bfe_u32 v5, v4, 16, 1
	v_add3_u32 v4, v4, v5, s88
	ds_write_b16_d16_hi v240, v4 offset:6528
	v_mul_f32_e32 v4, v55, v85
	v_mul_f32_e32 v4, v4, v84
	v_bfe_u32 v5, v4, 16, 1
	v_mul_f32_e32 v3, v3, v87
	v_add3_u32 v4, v4, v5, s88
	v_mul_f32_e32 v3, v81, v3
	ds_write_b16_d16_hi v240, v4 offset:6592
	v_bfe_u32 v6, v3, 16, 1
	v_add3_u32 v3, v3, v6, s88
	ds_write_b16_d16_hi v240, v3 offset:6656
	v_mul_f32_e32 v3, v19, v87
	v_mul_f32_e32 v3, v82, v3
	s_mov_b64 s[4:5], 0xd000
	v_bfe_u32 v6, v3, 16, 1
	v_lshl_add_u64 v[4:5], v[0:1], 0, s[4:5]
	v_add3_u32 v3, v3, v6, s88
	ds_write_b16_d16_hi v240, v3 offset:6720
	v_mul_f32_e32 v3, v35, v87
	v_mul_f32_e32 v3, v3, v83
	v_bfe_u32 v6, v3, 16, 1
	v_add3_u32 v3, v3, v6, s88
	ds_write_b16_d16_hi v240, v3 offset:6784
	v_mul_f32_e32 v3, v51, v87
	v_mul_f32_e32 v3, v3, v84
	v_bfe_u32 v6, v3, 16, 1
	v_mul_f32_e32 v2, v2, v86
	v_add3_u32 v3, v3, v6, s88
	v_mul_f32_e32 v2, v81, v2
	ds_write_b16_d16_hi v240, v3 offset:6848
	v_bfe_u32 v3, v2, 16, 1
	v_add3_u32 v2, v2, v3, s88
	ds_write_b16_d16_hi v240, v2 offset:6912
	v_mul_f32_e32 v2, v18, v86
	v_mul_f32_e32 v2, v82, v2
	v_bfe_u32 v3, v2, 16, 1
	v_lshl_add_u64 v[0:1], v[0:1], 0, s[62:63]
	v_add3_u32 v2, v2, v3, s88
	ds_write_b16_d16_hi v240, v2 offset:6976
	v_mul_f32_e32 v2, v34, v86
	v_mul_f32_e32 v2, v83, v2
	v_bfe_u32 v3, v2, 16, 1
	v_add3_u32 v2, v2, v3, s88
	ds_write_b16_d16_hi v240, v2 offset:7040
	v_mul_f32_e32 v2, v52, v86
	v_mul_f32_e32 v2, v84, v2
	v_bfe_u32 v3, v2, 16, 1
	v_add3_u32 v2, v2, v3, s88
	ds_write_b16_d16_hi v240, v2 offset:7104
	s_waitcnt lgkmcnt(0)
	ds_read_b128 v[228:231], v241
	s_waitcnt lgkmcnt(0)
	global_store_dwordx4 v[242:243], v[228:231], off
	s_nop 1
	v_lshl_add_u64 v[242:243], v[242:243], 0, v[232:233]
	ds_read_b128 v[244:247], v241 offset:1024
	s_waitcnt lgkmcnt(0)
	global_store_dwordx4 v[242:243], v[244:247], off
	s_nop 1
	v_lshl_add_u64 v[242:243], v[242:243], 0, v[232:233]
	ds_read_b128 v[228:231], v241 offset:2048
	s_waitcnt lgkmcnt(0)
	global_store_dwordx4 v[242:243], v[228:231], off
	s_nop 1
	v_lshl_add_u64 v[242:243], v[242:243], 0, v[232:233]
	ds_read_b128 v[244:247], v241 offset:3072
	s_waitcnt lgkmcnt(0)
	global_store_dwordx4 v[242:243], v[244:247], off
	s_nop 1
	v_lshl_add_u64 v[242:243], v[242:243], 0, v[232:233]
	ds_read_b128 v[228:231], v241 offset:4096
	s_waitcnt lgkmcnt(0)
	global_store_dwordx4 v[242:243], v[228:231], off
	s_nop 1
	v_lshl_add_u64 v[242:243], v[242:243], 0, v[232:233]
	ds_read_b128 v[244:247], v241 offset:5120
	s_waitcnt lgkmcnt(0)
	global_store_dwordx4 v[242:243], v[244:247], off
	s_nop 1
	v_lshl_add_u64 v[242:243], v[242:243], 0, v[232:233]
	ds_read_b128 v[228:231], v241 offset:6144
	s_waitcnt lgkmcnt(0)
	global_store_dwordx4 v[242:243], v[228:231], off
	s_nop 1
	v_lshl_add_u64 v[242:243], v[242:243], 0, v[232:233]
	ds_read_b128 v[244:247], v241 offset:7168
	s_waitcnt lgkmcnt(0)
	global_store_dwordx4 v[242:243], v[244:247], off
	s_nop 1
	s_branch .LBB0_459
